# branch epilogue: flat->global ops + counted vmcnt waits (was full drains), loop-top lgkmcnt only
# speedup vs baseline: 1.0056x; 1.0056x over previous
.LBB0_1627:
	s_ashr_i32 s13, s47, 31
	s_lshr_b32 s13, s13, 21
	s_add_i32 s13, s47, s13
	s_ashr_i32 s18, s13, 11
	v_mov_b32_e32 v1, v182
	s_lshl_b32 s13, s48, 8
	v_lshl_add_u32 v150, s49, 8, v183
	v_and_b32_e32 v35, 1, v1
	s_or_b32 s13, s13, s35
	v_lshl_add_u32 v148, v1, 3, s13
	v_lshl_or_b32 v1, v35, 4, v150
	v_mov_b64_e32 v[36:37], s[6:7]
	s_movk_i32 s13, 0x3000
	v_mad_i64_i32 v[36:37], s[20:21], v1, s13, v[36:37]
	s_ashr_i32 s19, s18, 31
	v_lshlrev_b32_e32 v1, 3, v35
	s_lshl_b64 s[18:19], s[18:19], 12
	v_sub_u32_e32 v134, v148, v1
	v_lshl_add_u64 v[36:37], v[36:37], 0, s[18:19]
	v_ashrrev_i32_e32 v135, 31, v134
	v_lshl_add_u64 v[36:37], v[36:37], 0, v[134:135]
	global_load_dwordx4 v[134:137], v[36:37], off
	s_cmpk_gt_i32 s47, 0xfff
	s_mov_b64 s[18:19], -1
	s_cbranch_scc1 .LBB0_1630
	s_andn2_b64 vcc, exec, s[18:19]
	s_cbranch_vccz .LBB0_1631

.LBB0_1630:
	s_waitcnt vmcnt(0)
	v_mov_b32_e32 v1, v134
	v_mov_b32_e32 v35, v136
	v_mov_b32_e32 v158, v135
	v_mov_b32_e32 v160, v137
	v_permlane16_swap_b32_e32 v1, v35
	s_nop 0
	v_permlane16_swap_b32_e32 v158, v160
	v_ashrrev_i32_e32 v151, 31, v150
	v_cvt_f32_ubyte1_e32 v153, v1
	v_cvt_f32_ubyte0_e32 v152, v1
	s_mov_b32 s20, 0x3b808081
	v_cvt_f32_ubyte3_e32 v155, v1
	v_cvt_f32_ubyte2_e32 v154, v1
	v_cvt_f32_ubyte1_e32 v157, v158
	v_cvt_f32_ubyte0_e32 v156, v158
	v_cvt_f32_ubyte3_e32 v159, v158
	v_cvt_f32_ubyte2_e32 v158, v158
	v_pk_mul_f32 v[152:153], v[152:153], s[20:21] op_sel_hi:[1,0]
	v_pk_mul_f32 v[154:155], v[154:155], s[20:21] op_sel_hi:[1,0]
	v_pk_mul_f32 v[156:157], v[156:157], s[20:21] op_sel_hi:[1,0]
	v_pk_mul_f32 v[158:159], v[158:159], s[20:21] op_sel_hi:[1,0]
	v_lshlrev_b64 v[150:151], 13, v[150:151]
	v_ashrrev_i32_e32 v149, 31, v148
	v_add_co_u32_e32 v146, vcc, 0x60000, v36
	v_pk_mul_f32 v[152:153], v[130:131], v[152:153]
	v_pk_mul_f32 v[154:155], v[132:133], v[154:155]
	v_pk_mul_f32 v[156:157], v[126:127], v[156:157]
	v_pk_mul_f32 v[158:159], v[128:129], v[158:159]
	v_lshl_add_u64 v[150:151], s[8:9], 0, v[150:151]
	v_addc_co_u32_e32 v147, vcc, 0, v37, vcc
	v_cvt_pk_bf16_f32 v152, v152, v153
	v_cvt_pk_bf16_f32 v153, v154, v155
	v_cvt_pk_bf16_f32 v154, v156, v157
	v_cvt_pk_bf16_f32 v155, v158, v159
	v_lshl_add_u64 v[150:151], v[148:149], 1, v[150:151]
	global_load_dwordx4 v[138:141], v[36:37], off offset:128
	global_load_dwordx4 v[142:145], v[146:147], off
	v_cvt_f32_ubyte1_e32 v149, v35
	global_store_dwordx4 v[150:151], v[152:155], off
	v_cvt_f32_ubyte0_e32 v148, v35
	v_pk_mul_f32 v[148:149], v[148:149], s[20:21] op_sel_hi:[1,0]
	v_cvt_f32_ubyte3_e32 v153, v35
	v_cvt_f32_ubyte2_e32 v152, v35
	v_pk_mul_f32 v[152:153], v[152:153], s[20:21] op_sel_hi:[1,0]
	v_pk_mul_f32 v[148:149], v[122:123], v[148:149]
	v_pk_mul_f32 v[154:155], v[124:125], v[152:153]
	v_cvt_f32_ubyte1_e32 v153, v160
	v_cvt_f32_ubyte0_e32 v152, v160
	v_pk_mul_f32 v[152:153], v[152:153], s[20:21] op_sel_hi:[1,0]
	s_mov_b32 s13, 0x20000
	v_pk_mul_f32 v[156:157], v[118:119], v[152:153]
	v_cvt_f32_ubyte3_e32 v153, v160
	v_cvt_f32_ubyte2_e32 v152, v160
	v_pk_mul_f32 v[152:153], v[152:153], s[20:21] op_sel_hi:[1,0]
	s_mov_b64 s[18:19], 0x20000
	v_pk_mul_f32 v[158:159], v[120:121], v[152:153]
	v_cvt_pk_bf16_f32 v152, v148, v149
	v_add_co_u32_e32 v148, vcc, s13, v150
	v_cvt_pk_bf16_f32 v153, v154, v155
	v_cvt_pk_bf16_f32 v154, v156, v157
	v_cvt_pk_bf16_f32 v155, v158, v159
	v_addc_co_u32_e32 v149, vcc, 0, v151, vcc
	global_store_dwordx4 v[148:149], v[152:155], off
	s_waitcnt vmcnt(3)
	global_load_dwordx4 v[146:149], v[146:147], off offset:128
	v_mov_b32_e32 v1, v140
	v_mov_b32_e32 v35, v141
	s_nop 0
	v_permlane16_swap_b32_e32 v138, v1
	v_permlane16_swap_b32_e32 v139, v35
	v_cvt_f32_ubyte1_e32 v141, v138
	v_cvt_f32_ubyte0_e32 v140, v138
	v_cvt_f32_ubyte3_e32 v153, v138
	v_cvt_f32_ubyte2_e32 v152, v138
	v_cvt_f32_ubyte1_e32 v155, v139
	v_cvt_f32_ubyte0_e32 v154, v139
	v_cvt_f32_ubyte3_e32 v159, v139
	v_cvt_f32_ubyte2_e32 v158, v139
	v_pk_mul_f32 v[140:141], v[140:141], s[20:21] op_sel_hi:[1,0]
	v_pk_mul_f32 v[152:153], v[152:153], s[20:21] op_sel_hi:[1,0]
	v_pk_mul_f32 v[154:155], v[154:155], s[20:21] op_sel_hi:[1,0]
	v_pk_mul_f32 v[138:139], v[158:159], s[20:21] op_sel_hi:[1,0]
	v_pk_mul_f32 v[140:141], v[98:99], v[140:141]
	v_pk_mul_f32 v[152:153], v[100:101], v[152:153]
	v_pk_mul_f32 v[154:155], v[94:95], v[154:155]
	v_pk_mul_f32 v[158:159], v[96:97], v[138:139]
	v_cvt_pk_bf16_f32 v138, v140, v141
	v_cvt_pk_bf16_f32 v139, v152, v153
	v_cvt_pk_bf16_f32 v140, v154, v155
	v_cvt_pk_bf16_f32 v141, v158, v159
	global_store_dwordx4 v[150:151], v[138:141], off offset:256
	v_cvt_f32_ubyte1_e32 v153, v35
	v_cvt_f32_ubyte0_e32 v152, v35
	v_cvt_f32_ubyte1_e32 v139, v1
	v_cvt_f32_ubyte0_e32 v138, v1
	v_cvt_f32_ubyte3_e32 v141, v1
	v_cvt_f32_ubyte2_e32 v140, v1
	v_cvt_f32_ubyte3_e32 v155, v35
	v_cvt_f32_ubyte2_e32 v154, v35
	v_pk_mul_f32 v[138:139], v[138:139], s[20:21] op_sel_hi:[1,0]
	v_pk_mul_f32 v[140:141], v[140:141], s[20:21] op_sel_hi:[1,0]
	v_pk_mul_f32 v[152:153], v[152:153], s[20:21] op_sel_hi:[1,0]
	v_pk_mul_f32 v[154:155], v[154:155], s[20:21] op_sel_hi:[1,0]
	v_pk_mul_f32 v[138:139], v[90:91], v[138:139]
	v_pk_mul_f32 v[140:141], v[92:93], v[140:141]
	v_pk_mul_f32 v[152:153], v[86:87], v[152:153]
	v_pk_mul_f32 v[154:155], v[88:89], v[154:155]
	v_lshl_add_u64 v[156:157], v[150:151], 0, s[18:19]
	v_cvt_pk_bf16_f32 v138, v138, v139
	v_cvt_pk_bf16_f32 v139, v140, v141
	v_cvt_pk_bf16_f32 v140, v152, v153
	v_cvt_pk_bf16_f32 v141, v154, v155
	global_store_dwordx4 v[156:157], v[138:141], off offset:256
	s_waitcnt vmcnt(5)
	s_mov_b32 s13, 0x180000
	v_mov_b32_e32 v1, v144
	v_mov_b32_e32 v35, v145
	s_nop 0
	v_permlane16_swap_b32_e32 v142, v1
	v_permlane16_swap_b32_e32 v143, v35
	v_cvt_f32_ubyte1_e32 v145, v142
	v_cvt_f32_ubyte0_e32 v144, v142
	v_cvt_f32_ubyte1_e32 v157, v143
	v_cvt_f32_ubyte0_e32 v156, v143
	v_add_co_u32_e32 v152, vcc, s13, v36
	v_pk_mul_f32 v[144:145], v[144:145], s[20:21] op_sel_hi:[1,0]
	v_cvt_f32_ubyte3_e32 v155, v142
	v_cvt_f32_ubyte2_e32 v154, v142
	v_pk_mul_f32 v[156:157], v[156:157], s[20:21] op_sel_hi:[1,0]
	v_cvt_f32_ubyte3_e32 v159, v143
	v_cvt_f32_ubyte2_e32 v158, v143
	v_addc_co_u32_e32 v153, vcc, 0, v37, vcc
	v_pk_mul_f32 v[144:145], v[114:115], v[144:145]
	v_pk_mul_f32 v[154:155], v[154:155], s[20:21] op_sel_hi:[1,0]
	v_pk_mul_f32 v[156:157], v[110:111], v[156:157]
	v_pk_mul_f32 v[142:143], v[158:159], s[20:21] op_sel_hi:[1,0]
	s_mov_b32 s13, 0x40000
	v_pk_mul_f32 v[154:155], v[116:117], v[154:155]
	v_pk_mul_f32 v[158:159], v[112:113], v[142:143]
	v_cvt_pk_bf16_f32 v142, v144, v145
	v_cvt_pk_bf16_f32 v144, v156, v157
	v_add_co_u32_e32 v156, vcc, s13, v150
	v_cvt_pk_bf16_f32 v143, v154, v155
	v_cvt_pk_bf16_f32 v145, v158, v159
	v_addc_co_u32_e32 v157, vcc, 0, v151, vcc
	global_load_dwordx4 v[138:141], v[152:153], off
	v_cvt_f32_ubyte3_e32 v159, v35
	global_store_dwordx4 v[156:157], v[142:145], off
	v_cvt_f32_ubyte2_e32 v158, v35
	v_cvt_f32_ubyte1_e32 v157, v35
	v_cvt_f32_ubyte1_e32 v143, v1
	v_cvt_f32_ubyte0_e32 v142, v1
	v_cvt_f32_ubyte3_e32 v145, v1
	v_cvt_f32_ubyte2_e32 v144, v1
	v_pk_mul_f32 v[142:143], v[142:143], s[20:21] op_sel_hi:[1,0]
	v_pk_mul_f32 v[144:145], v[144:145], s[20:21] op_sel_hi:[1,0]
	v_cvt_f32_ubyte0_e32 v156, v35
	v_pk_mul_f32 v[158:159], v[158:159], s[20:21] op_sel_hi:[1,0]
	v_pk_mul_f32 v[142:143], v[106:107], v[142:143]
	v_pk_mul_f32 v[144:145], v[108:109], v[144:145]
	v_pk_mul_f32 v[156:157], v[156:157], s[20:21] op_sel_hi:[1,0]
	v_pk_mul_f32 v[158:159], v[104:105], v[158:159]
	s_mov_b32 s13, 0x60000
	v_pk_mul_f32 v[156:157], v[102:103], v[156:157]
	v_cvt_pk_bf16_f32 v142, v142, v143
	v_cvt_pk_bf16_f32 v143, v144, v145
	v_cvt_pk_bf16_f32 v145, v158, v159
	v_add_co_u32_e32 v158, vcc, s13, v150
	v_cvt_pk_bf16_f32 v144, v156, v157
	s_nop 0
	v_addc_co_u32_e32 v159, vcc, 0, v151, vcc
	global_store_dwordx4 v[158:159], v[142:145], off
	s_waitcnt vmcnt(5)
	global_load_dwordx4 v[142:145], v[152:153], off offset:128
	v_mov_b32_e32 v1, v148
	v_mov_b32_e32 v35, v149
	s_nop 0
	v_permlane16_swap_b32_e32 v146, v1
	v_permlane16_swap_b32_e32 v147, v35
	v_cvt_f32_ubyte1_e32 v149, v146
	v_cvt_f32_ubyte0_e32 v148, v146
	v_cvt_f32_ubyte3_e32 v153, v146
	v_cvt_f32_ubyte2_e32 v152, v146
	v_cvt_f32_ubyte1_e32 v159, v147
	v_cvt_f32_ubyte0_e32 v158, v147
	v_cvt_f32_ubyte3_e32 v161, v147
	v_cvt_f32_ubyte2_e32 v160, v147
	v_pk_mul_f32 v[148:149], v[148:149], s[20:21] op_sel_hi:[1,0]
	v_pk_mul_f32 v[152:153], v[152:153], s[20:21] op_sel_hi:[1,0]
	v_pk_mul_f32 v[158:159], v[158:159], s[20:21] op_sel_hi:[1,0]
	v_pk_mul_f32 v[146:147], v[160:161], s[20:21] op_sel_hi:[1,0]
	s_mov_b64 s[18:19], 0x40000
	v_pk_mul_f32 v[148:149], v[82:83], v[148:149]
	v_pk_mul_f32 v[152:153], v[84:85], v[152:153]
	v_pk_mul_f32 v[158:159], v[78:79], v[158:159]
	v_pk_mul_f32 v[160:161], v[80:81], v[146:147]
	v_lshl_add_u64 v[154:155], v[150:151], 0, s[18:19]
	v_cvt_pk_bf16_f32 v146, v148, v149
	v_cvt_pk_bf16_f32 v147, v152, v153
	v_cvt_pk_bf16_f32 v148, v158, v159
	v_cvt_pk_bf16_f32 v149, v160, v161
	global_store_dwordx4 v[154:155], v[146:149], off offset:256
	v_cvt_f32_ubyte1_e32 v153, v35
	v_cvt_f32_ubyte0_e32 v152, v35
	v_cvt_f32_ubyte1_e32 v147, v1
	v_cvt_f32_ubyte0_e32 v146, v1
	v_cvt_f32_ubyte3_e32 v149, v1
	v_cvt_f32_ubyte2_e32 v148, v1
	v_cvt_f32_ubyte3_e32 v155, v35
	v_cvt_f32_ubyte2_e32 v154, v35
	v_pk_mul_f32 v[146:147], v[146:147], s[20:21] op_sel_hi:[1,0]
	v_pk_mul_f32 v[148:149], v[148:149], s[20:21] op_sel_hi:[1,0]
	v_pk_mul_f32 v[152:153], v[152:153], s[20:21] op_sel_hi:[1,0]
	v_pk_mul_f32 v[154:155], v[154:155], s[20:21] op_sel_hi:[1,0]
	s_mov_b64 s[18:19], 0x60000
	v_pk_mul_f32 v[146:147], v[74:75], v[146:147]
	v_pk_mul_f32 v[148:149], v[76:77], v[148:149]
	v_pk_mul_f32 v[152:153], v[70:71], v[152:153]
	v_pk_mul_f32 v[154:155], v[72:73], v[154:155]
	v_lshl_add_u64 v[156:157], v[150:151], 0, s[18:19]
	v_cvt_pk_bf16_f32 v146, v146, v147
	v_cvt_pk_bf16_f32 v147, v148, v149
	v_cvt_pk_bf16_f32 v148, v152, v153
	v_cvt_pk_bf16_f32 v149, v154, v155
	global_store_dwordx4 v[156:157], v[146:149], off offset:256
	s_waitcnt vmcnt(5)
	s_mov_b32 s13, 0x1e0000
	v_mov_b32_e32 v1, v140
	v_mov_b32_e32 v35, v141
	s_nop 0
	v_permlane16_swap_b32_e32 v138, v1
	v_permlane16_swap_b32_e32 v139, v35
	v_cvt_f32_ubyte1_e32 v141, v138
	v_cvt_f32_ubyte0_e32 v140, v138
	v_cvt_f32_ubyte1_e32 v157, v139
	v_cvt_f32_ubyte0_e32 v156, v139
	v_add_co_u32_e32 v152, vcc, s13, v36
	v_pk_mul_f32 v[140:141], v[140:141], s[20:21] op_sel_hi:[1,0]
	v_cvt_f32_ubyte3_e32 v155, v138
	v_cvt_f32_ubyte2_e32 v154, v138
	v_pk_mul_f32 v[156:157], v[156:157], s[20:21] op_sel_hi:[1,0]
	v_cvt_f32_ubyte3_e32 v159, v139
	v_cvt_f32_ubyte2_e32 v158, v139
	v_addc_co_u32_e32 v153, vcc, 0, v37, vcc
	v_pk_mul_f32 v[140:141], v[66:67], v[140:141]
	v_pk_mul_f32 v[154:155], v[154:155], s[20:21] op_sel_hi:[1,0]
	v_pk_mul_f32 v[156:157], v[62:63], v[156:157]
	v_pk_mul_f32 v[138:139], v[158:159], s[20:21] op_sel_hi:[1,0]
	s_mov_b32 s13, 0x100000
	v_pk_mul_f32 v[154:155], v[68:69], v[154:155]
	v_pk_mul_f32 v[158:159], v[64:65], v[138:139]
	v_cvt_pk_bf16_f32 v138, v140, v141
	v_cvt_pk_bf16_f32 v140, v156, v157
	v_add_co_u32_e32 v156, vcc, s13, v150
	v_cvt_pk_bf16_f32 v139, v154, v155
	v_cvt_pk_bf16_f32 v141, v158, v159
	v_addc_co_u32_e32 v157, vcc, 0, v151, vcc
	global_load_dwordx4 v[146:149], v[152:153], off
	v_cvt_f32_ubyte3_e32 v159, v35
	global_store_dwordx4 v[156:157], v[138:141], off
	v_cvt_f32_ubyte2_e32 v158, v35
	v_cvt_f32_ubyte1_e32 v157, v35
	v_cvt_f32_ubyte1_e32 v139, v1
	v_cvt_f32_ubyte0_e32 v138, v1
	v_cvt_f32_ubyte3_e32 v141, v1
	v_cvt_f32_ubyte2_e32 v140, v1
	v_pk_mul_f32 v[138:139], v[138:139], s[20:21] op_sel_hi:[1,0]
	v_pk_mul_f32 v[140:141], v[140:141], s[20:21] op_sel_hi:[1,0]
	v_cvt_f32_ubyte0_e32 v156, v35
	v_pk_mul_f32 v[158:159], v[158:159], s[20:21] op_sel_hi:[1,0]
	v_pk_mul_f32 v[138:139], v[58:59], v[138:139]
	v_pk_mul_f32 v[140:141], v[60:61], v[140:141]
	v_pk_mul_f32 v[156:157], v[156:157], s[20:21] op_sel_hi:[1,0]
	v_pk_mul_f32 v[158:159], v[56:57], v[158:159]
	s_mov_b32 s13, 0x120000
	v_pk_mul_f32 v[156:157], v[54:55], v[156:157]
	v_cvt_pk_bf16_f32 v138, v138, v139
	v_cvt_pk_bf16_f32 v139, v140, v141
	v_cvt_pk_bf16_f32 v141, v158, v159
	v_add_co_u32_e32 v158, vcc, s13, v150
	v_cvt_pk_bf16_f32 v140, v156, v157
	s_nop 0
	v_addc_co_u32_e32 v159, vcc, 0, v151, vcc
	global_store_dwordx4 v[158:159], v[138:141], off
	s_waitcnt vmcnt(5)
	global_load_dwordx4 v[138:141], v[152:153], off offset:128
	v_mov_b32_e32 v1, v144
	v_mov_b32_e32 v35, v145
	s_nop 0
	v_permlane16_swap_b32_e32 v142, v1
	v_permlane16_swap_b32_e32 v143, v35
	v_cvt_f32_ubyte1_e32 v145, v142
	v_cvt_f32_ubyte0_e32 v144, v142
	v_cvt_f32_ubyte3_e32 v153, v142
	v_cvt_f32_ubyte2_e32 v152, v142
	v_cvt_f32_ubyte1_e32 v159, v143
	v_cvt_f32_ubyte0_e32 v158, v143
	v_cvt_f32_ubyte3_e32 v161, v143
	v_cvt_f32_ubyte2_e32 v160, v143
	v_pk_mul_f32 v[144:145], v[144:145], s[20:21] op_sel_hi:[1,0]
	v_pk_mul_f32 v[152:153], v[152:153], s[20:21] op_sel_hi:[1,0]
	v_pk_mul_f32 v[158:159], v[158:159], s[20:21] op_sel_hi:[1,0]
	v_pk_mul_f32 v[142:143], v[160:161], s[20:21] op_sel_hi:[1,0]
	s_mov_b64 s[18:19], 0x100000
	v_pk_mul_f32 v[144:145], v[30:31], v[144:145]
	v_pk_mul_f32 v[152:153], v[32:33], v[152:153]
	v_pk_mul_f32 v[158:159], v[26:27], v[158:159]
	v_pk_mul_f32 v[160:161], v[28:29], v[142:143]
	v_lshl_add_u64 v[154:155], v[150:151], 0, s[18:19]
	v_cvt_pk_bf16_f32 v142, v144, v145
	v_cvt_pk_bf16_f32 v143, v152, v153
	v_cvt_pk_bf16_f32 v144, v158, v159
	v_cvt_pk_bf16_f32 v145, v160, v161
	global_store_dwordx4 v[154:155], v[142:145], off offset:256
	v_cvt_f32_ubyte1_e32 v153, v35
	v_cvt_f32_ubyte0_e32 v152, v35
	v_cvt_f32_ubyte1_e32 v143, v1
	v_cvt_f32_ubyte0_e32 v142, v1
	v_cvt_f32_ubyte3_e32 v145, v1
	v_cvt_f32_ubyte2_e32 v144, v1
	v_cvt_f32_ubyte3_e32 v155, v35
	v_cvt_f32_ubyte2_e32 v154, v35
	v_pk_mul_f32 v[142:143], v[142:143], s[20:21] op_sel_hi:[1,0]
	v_pk_mul_f32 v[144:145], v[144:145], s[20:21] op_sel_hi:[1,0]
	v_pk_mul_f32 v[152:153], v[152:153], s[20:21] op_sel_hi:[1,0]
	v_pk_mul_f32 v[154:155], v[154:155], s[20:21] op_sel_hi:[1,0]
	s_mov_b64 s[18:19], 0x120000
	v_pk_mul_f32 v[142:143], v[22:23], v[142:143]
	v_pk_mul_f32 v[144:145], v[24:25], v[144:145]
	v_pk_mul_f32 v[152:153], v[18:19], v[152:153]
	v_pk_mul_f32 v[154:155], v[20:21], v[154:155]
	v_lshl_add_u64 v[156:157], v[150:151], 0, s[18:19]
	v_cvt_pk_bf16_f32 v142, v142, v143
	v_cvt_pk_bf16_f32 v143, v144, v145
	v_cvt_pk_bf16_f32 v144, v152, v153
	v_cvt_pk_bf16_f32 v145, v154, v155
	global_store_dwordx4 v[156:157], v[142:145], off offset:256
	s_waitcnt vmcnt(2)
	s_mov_b32 s13, 0x140000
	v_mov_b32_e32 v1, v148
	v_mov_b32_e32 v35, v149
	s_nop 0
	v_permlane16_swap_b32_e32 v146, v1
	v_permlane16_swap_b32_e32 v147, v35
	v_cvt_f32_ubyte1_e32 v143, v146
	v_cvt_f32_ubyte0_e32 v142, v146
	v_cvt_f32_ubyte3_e32 v145, v146
	v_cvt_f32_ubyte2_e32 v144, v146
	v_cvt_f32_ubyte3_e32 v153, v147
	v_cvt_f32_ubyte2_e32 v152, v147
	v_pk_mul_f32 v[142:143], v[142:143], s[20:21] op_sel_hi:[1,0]
	v_pk_mul_f32 v[144:145], v[144:145], s[20:21] op_sel_hi:[1,0]
	v_cvt_f32_ubyte1_e32 v149, v147
	v_cvt_f32_ubyte0_e32 v148, v147
	v_pk_mul_f32 v[146:147], v[152:153], s[20:21] op_sel_hi:[1,0]
	v_pk_mul_f32 v[142:143], v[50:51], v[142:143]
	v_pk_mul_f32 v[144:145], v[52:53], v[144:145]
	v_pk_mul_f32 v[148:149], v[148:149], s[20:21] op_sel_hi:[1,0]
	v_pk_mul_f32 v[146:147], v[48:49], v[146:147]
	v_pk_mul_f32 v[148:149], v[46:47], v[148:149]
	v_cvt_pk_bf16_f32 v142, v142, v143
	v_cvt_pk_bf16_f32 v143, v144, v145
	v_cvt_pk_bf16_f32 v145, v146, v147
	v_add_co_u32_e32 v146, vcc, s13, v150
	v_cvt_pk_bf16_f32 v144, v148, v149
	s_nop 0
	v_addc_co_u32_e32 v147, vcc, 0, v151, vcc
	global_store_dwordx4 v[146:147], v[142:145], off
	v_cvt_f32_ubyte1_e32 v147, v35
	v_cvt_f32_ubyte0_e32 v146, v35
	v_cvt_f32_ubyte1_e32 v143, v1
	v_cvt_f32_ubyte0_e32 v142, v1
	v_cvt_f32_ubyte3_e32 v145, v1
	v_cvt_f32_ubyte2_e32 v144, v1
	s_mov_b64 s[18:19], 0x140000
	v_pk_mul_f32 v[142:143], v[142:143], s[20:21] op_sel_hi:[1,0]
	v_pk_mul_f32 v[144:145], v[144:145], s[20:21] op_sel_hi:[1,0]
	v_pk_mul_f32 v[146:147], v[146:147], s[20:21] op_sel_hi:[1,0]
	v_cvt_f32_ubyte3_e32 v153, v35
	v_cvt_f32_ubyte2_e32 v152, v35
	v_lshl_add_u64 v[148:149], v[150:151], 0, s[18:19]
	v_pk_mul_f32 v[142:143], v[42:43], v[142:143]
	v_pk_mul_f32 v[144:145], v[44:45], v[144:145]
	v_pk_mul_f32 v[146:147], v[38:39], v[146:147]
	v_pk_mul_f32 v[152:153], v[152:153], s[20:21] op_sel_hi:[1,0]
	s_mov_b64 s[18:19], 0x160000
	s_mov_b32 s13, 0x160000
	v_pk_mul_f32 v[152:153], v[40:41], v[152:153]
	v_cvt_pk_bf16_f32 v142, v142, v143
	v_cvt_pk_bf16_f32 v143, v144, v145
	v_cvt_pk_bf16_f32 v144, v146, v147
	v_lshl_add_u64 v[146:147], v[150:151], 0, s[18:19]
	v_add_co_u32_e32 v150, vcc, s13, v150
	v_cvt_pk_bf16_f32 v145, v152, v153
	s_nop 0
	v_addc_co_u32_e32 v151, vcc, 0, v151, vcc
	global_store_dwordx4 v[150:151], v[142:145], off
	s_nop 1
	v_mov_b64_e32 v[144:145], v[140:141]
	v_mov_b64_e32 v[142:143], v[138:139]
	s_nop 0
	v_mov_b32_e32 v1, v140
	v_mov_b32_e32 v35, v141
	s_nop 0
	v_permlane16_swap_b32_e32 v138, v1
	v_permlane16_swap_b32_e32 v139, v35
	v_cvt_f32_ubyte1_e32 v141, v138
	v_cvt_f32_ubyte0_e32 v140, v138
	v_cvt_f32_ubyte3_e32 v151, v138
	v_cvt_f32_ubyte2_e32 v150, v138
	v_cvt_f32_ubyte1_e32 v153, v139
	v_cvt_f32_ubyte0_e32 v152, v139
	v_cvt_f32_ubyte3_e32 v155, v139
	v_cvt_f32_ubyte2_e32 v154, v139
	v_pk_mul_f32 v[140:141], v[140:141], s[20:21] op_sel_hi:[1,0]
	v_pk_mul_f32 v[150:151], v[150:151], s[20:21] op_sel_hi:[1,0]
	v_pk_mul_f32 v[152:153], v[152:153], s[20:21] op_sel_hi:[1,0]
	v_pk_mul_f32 v[138:139], v[154:155], s[20:21] op_sel_hi:[1,0]
	v_pk_mul_f32 v[140:141], v[14:15], v[140:141]
	v_pk_mul_f32 v[150:151], v[16:17], v[150:151]
	v_pk_mul_f32 v[152:153], v[10:11], v[152:153]
	v_pk_mul_f32 v[154:155], v[12:13], v[138:139]
	v_cvt_pk_bf16_f32 v138, v140, v141
	v_cvt_pk_bf16_f32 v139, v150, v151
	v_cvt_pk_bf16_f32 v140, v152, v153
	v_cvt_pk_bf16_f32 v141, v154, v155
	global_store_dwordx4 v[148:149], v[138:141], off offset:256
	v_cvt_f32_ubyte1_e32 v149, v35
	v_cvt_f32_ubyte0_e32 v148, v35
	v_cvt_f32_ubyte1_e32 v139, v1
	v_cvt_f32_ubyte0_e32 v138, v1
	v_cvt_f32_ubyte3_e32 v141, v1
	v_cvt_f32_ubyte2_e32 v140, v1
	v_cvt_f32_ubyte3_e32 v151, v35
	v_cvt_f32_ubyte2_e32 v150, v35
	v_pk_mul_f32 v[138:139], v[138:139], s[20:21] op_sel_hi:[1,0]
	v_pk_mul_f32 v[140:141], v[140:141], s[20:21] op_sel_hi:[1,0]
	v_pk_mul_f32 v[148:149], v[148:149], s[20:21] op_sel_hi:[1,0]
	v_pk_mul_f32 v[150:151], v[150:151], s[20:21] op_sel_hi:[1,0]
	v_pk_mul_f32 v[138:139], v[6:7], v[138:139]
	v_pk_mul_f32 v[140:141], v[8:9], v[140:141]
	v_pk_mul_f32 v[148:149], v[2:3], v[148:149]
	v_pk_mul_f32 v[150:151], v[4:5], v[150:151]
	v_cvt_pk_bf16_f32 v138, v138, v139
	v_cvt_pk_bf16_f32 v139, v140, v141
	v_cvt_pk_bf16_f32 v140, v148, v149
	v_cvt_pk_bf16_f32 v141, v150, v151
	global_store_dwordx4 v[146:147], v[138:141], off offset:256
	s_nop 1
	v_mov_b64_e32 v[138:139], v[142:143]
	v_mov_b64_e32 v[140:141], v[144:145]
	s_cbranch_execnz .LBB0_1629
.LBB0_1631:
	v_add_co_u32_e32 v138, vcc, 0x1000, v36
	s_waitcnt vmcnt(0)
	v_mov_b32_e32 v1, v136
	v_addc_co_u32_e32 v139, vcc, 0, v37, vcc
	global_load_dwordx4 v[158:161], v[138:139], off
	global_load_dwordx4 v[146:149], v[36:37], off offset:128
	global_load_dwordx4 v[150:153], v[138:139], off offset:128
	v_mov_b32_e32 v35, v137
	v_permlane16_swap_b32_e32 v134, v1
	v_cvt_f32_ubyte1_e32 v189, v134
	v_cvt_f32_ubyte0_e32 v188, v134
	v_cvt_f32_ubyte3_e32 v187, v134
	v_cvt_f32_ubyte2_e32 v186, v134
	v_permlane16_swap_b32_e32 v135, v35
	v_add_co_u32_e32 v154, vcc, 0x61000, v36
	s_mov_b32 s13, 0x181000
	s_nop 0
	v_addc_co_u32_e32 v155, vcc, 0, v37, vcc
	v_add_co_u32_e32 v156, vcc, 0x60000, v36
	global_load_dwordx4 v[138:141], v[154:155], off
	s_nop 0
	v_addc_co_u32_e32 v157, vcc, 0, v37, vcc
	global_load_dwordx4 v[142:145], v[156:157], off
	s_waitcnt vmcnt(2)
	v_mov_b32_e32 v190, v160
	s_nop 1
	v_permlane16_swap_b32_e32 v158, v190
	v_cvt_f32_ubyte0_e32 v136, v158
	v_cvt_f32_ubyte1_e32 v137, v158
	v_rcp_iflag_f32_e32 v136, v136
	v_rcp_iflag_f32_e32 v137, v137
	v_mov_b32_e32 v191, v161
	s_nop 1
	v_permlane16_swap_b32_e32 v159, v191
	v_pk_mul_f32 v[136:137], v[136:137], v[188:189]
	v_cvt_f32_ubyte0_e32 v134, v159
	v_cvt_f32_ubyte2_e32 v160, v158
	v_cvt_f32_ubyte3_e32 v158, v158
	v_pk_mul_f32 v[130:131], v[130:131], v[136:137]
	v_rcp_iflag_f32_e32 v136, v134
	v_cvt_f32_ubyte1_e32 v134, v159
	v_rcp_iflag_f32_e32 v160, v160
	v_rcp_iflag_f32_e32 v161, v158
	v_rcp_iflag_f32_e32 v137, v134
	v_cvt_f32_ubyte2_e32 v134, v159
	v_rcp_iflag_f32_e32 v158, v134
	v_cvt_f32_ubyte3_e32 v134, v159
	v_rcp_iflag_f32_e32 v159, v134
	v_pk_mul_f32 v[160:161], v[160:161], v[186:187]
	v_cvt_f32_ubyte1_e32 v187, v135
	v_pk_mul_f32 v[132:133], v[132:133], v[160:161]
	v_cvt_f32_ubyte3_e32 v161, v135
	v_cvt_f32_ubyte2_e32 v160, v135
	v_cvt_f32_ubyte0_e32 v186, v135
	v_pk_mul_f32 v[134:135], v[136:137], v[186:187]
	v_pk_mul_f32 v[136:137], v[158:159], v[160:161]
	v_pk_mul_f32 v[126:127], v[126:127], v[134:135]
	v_pk_mul_f32 v[128:129], v[128:129], v[136:137]
	v_cvt_f32_ubyte2_e32 v136, v190
	v_cvt_f32_ubyte3_e32 v137, v190
	v_rcp_iflag_f32_e32 v136, v136
	v_rcp_iflag_f32_e32 v137, v137
	v_cvt_f32_ubyte0_e32 v134, v190
	v_cvt_f32_ubyte1_e32 v135, v190
	v_rcp_iflag_f32_e32 v134, v134
	v_rcp_iflag_f32_e32 v135, v135
	v_cvt_f32_ubyte3_e32 v159, v1
	v_cvt_f32_ubyte2_e32 v158, v1
	v_cvt_f32_ubyte1_e32 v161, v1
	v_cvt_f32_ubyte0_e32 v160, v1
	v_pk_mul_f32 v[136:137], v[136:137], v[158:159]
	v_cvt_f32_ubyte0_e32 v1, v191
	v_pk_mul_f32 v[124:125], v[124:125], v[136:137]
	v_rcp_iflag_f32_e32 v136, v1
	v_cvt_f32_ubyte1_e32 v1, v191
	v_pk_mul_f32 v[134:135], v[134:135], v[160:161]
	v_rcp_iflag_f32_e32 v137, v1
	v_cvt_f32_ubyte2_e32 v1, v191
	v_pk_mul_f32 v[122:123], v[122:123], v[134:135]
	v_rcp_iflag_f32_e32 v134, v1
	v_cvt_f32_ubyte3_e32 v1, v191
	v_rcp_iflag_f32_e32 v135, v1
	v_cvt_f32_ubyte3_e32 v159, v35
	v_cvt_f32_ubyte2_e32 v158, v35
	v_cvt_f32_ubyte1_e32 v161, v35
	v_cvt_f32_ubyte0_e32 v160, v35
	v_pk_mul_f32 v[136:137], v[136:137], v[160:161]
	v_pk_mul_f32 v[134:135], v[134:135], v[158:159]
	v_pk_mul_f32 v[118:119], v[118:119], v[136:137]
	v_pk_mul_f32 v[120:121], v[120:121], v[134:135]
	s_nop 0
	global_load_dwordx4 v[158:161], v[154:155], off offset:128
	s_nop 0
	global_load_dwordx4 v[154:157], v[156:157], off offset:128
	v_mov_b32_e32 v186, v152
	s_nop 1
	v_permlane16_swap_b32_e32 v150, v186
	v_cvt_f32_ubyte0_e32 v134, v150
	v_cvt_f32_ubyte1_e32 v135, v150
	v_rcp_iflag_f32_e32 v134, v134
	v_rcp_iflag_f32_e32 v135, v135
	v_mov_b32_e32 v1, v148
	v_cvt_f32_ubyte2_e32 v136, v150
	v_cvt_f32_ubyte3_e32 v137, v150
	v_permlane16_swap_b32_e32 v146, v1
	v_rcp_iflag_f32_e32 v136, v136
	v_rcp_iflag_f32_e32 v137, v137
	v_mov_b32_e32 v187, v153
	v_cvt_f32_ubyte1_e32 v153, v146
	v_cvt_f32_ubyte0_e32 v152, v146
	v_permlane16_swap_b32_e32 v151, v187
	v_pk_mul_f32 v[134:135], v[134:135], v[152:153]
	v_mov_b32_e32 v35, v149
	v_cvt_f32_ubyte3_e32 v149, v146
	v_cvt_f32_ubyte2_e32 v148, v146
	v_pk_mul_f32 v[98:99], v[98:99], v[134:135]
	v_cvt_f32_ubyte0_e32 v134, v151
	v_cvt_f32_ubyte1_e32 v135, v151
	v_pk_mul_f32 v[136:137], v[136:137], v[148:149]
	v_rcp_iflag_f32_e32 v134, v134
	v_rcp_iflag_f32_e32 v135, v135
	v_pk_mul_f32 v[100:101], v[100:101], v[136:137]
	v_cvt_f32_ubyte2_e32 v136, v151
	v_cvt_f32_ubyte3_e32 v137, v151
	v_permlane16_swap_b32_e32 v147, v35
	v_rcp_iflag_f32_e32 v136, v136
	v_rcp_iflag_f32_e32 v137, v137
	v_cvt_f32_ubyte1_e32 v151, v147
	v_cvt_f32_ubyte0_e32 v150, v147
	v_pk_mul_f32 v[134:135], v[134:135], v[150:151]
	v_cvt_f32_ubyte3_e32 v149, v147
	v_cvt_f32_ubyte2_e32 v148, v147
	v_pk_mul_f32 v[94:95], v[94:95], v[134:135]
	v_cvt_f32_ubyte0_e32 v134, v186
	v_cvt_f32_ubyte1_e32 v135, v186
	v_pk_mul_f32 v[136:137], v[136:137], v[148:149]
	v_rcp_iflag_f32_e32 v134, v134
	v_rcp_iflag_f32_e32 v135, v135
	v_pk_mul_f32 v[96:97], v[96:97], v[136:137]
	v_cvt_f32_ubyte2_e32 v136, v186
	v_cvt_f32_ubyte3_e32 v137, v186
	v_rcp_iflag_f32_e32 v136, v136
	v_rcp_iflag_f32_e32 v137, v137
	v_cvt_f32_ubyte1_e32 v149, v1
	v_cvt_f32_ubyte0_e32 v148, v1
	v_cvt_f32_ubyte3_e32 v147, v1
	v_cvt_f32_ubyte2_e32 v146, v1
	v_pk_mul_f32 v[134:135], v[134:135], v[148:149]
	v_cvt_f32_ubyte0_e32 v1, v187
	v_pk_mul_f32 v[90:91], v[90:91], v[134:135]
	v_rcp_iflag_f32_e32 v134, v1
	v_cvt_f32_ubyte1_e32 v1, v187
	v_pk_mul_f32 v[136:137], v[136:137], v[146:147]
	v_rcp_iflag_f32_e32 v135, v1
	v_cvt_f32_ubyte2_e32 v1, v187
	v_pk_mul_f32 v[92:93], v[92:93], v[136:137]
	v_rcp_iflag_f32_e32 v136, v1
	v_cvt_f32_ubyte3_e32 v1, v187
	v_rcp_iflag_f32_e32 v137, v1
	v_cvt_f32_ubyte3_e32 v147, v35
	v_cvt_f32_ubyte2_e32 v146, v35
	v_cvt_f32_ubyte1_e32 v149, v35
	v_cvt_f32_ubyte0_e32 v148, v35
	v_pk_mul_f32 v[134:135], v[134:135], v[148:149]
	v_pk_mul_f32 v[136:137], v[136:137], v[146:147]
	v_pk_mul_f32 v[86:87], v[86:87], v[134:135]
	v_pk_mul_f32 v[88:89], v[88:89], v[136:137]
	v_add_co_u32_e32 v150, vcc, s13, v36
	s_waitcnt vmcnt(2)
	s_mov_b32 s13, 0x180000
	v_mov_b32_e32 v190, v140
	s_nop 1
	v_permlane16_swap_b32_e32 v138, v190
	v_mov_b32_e32 v191, v141
	v_cvt_f32_ubyte0_e32 v140, v138
	v_cvt_f32_ubyte1_e32 v141, v138
	v_rcp_iflag_f32_e32 v140, v140
	v_rcp_iflag_f32_e32 v141, v141
	v_mov_b32_e32 v1, v144
	s_nop 1
	v_permlane16_swap_b32_e32 v142, v1
	v_permlane16_swap_b32_e32 v139, v191
	v_cvt_f32_ubyte2_e32 v144, v138
	v_cvt_f32_ubyte3_e32 v138, v138
	v_cvt_f32_ubyte1_e32 v189, v142
	v_cvt_f32_ubyte0_e32 v188, v142
	v_mov_b32_e32 v35, v145
	v_rcp_iflag_f32_e32 v145, v138
	v_pk_mul_f32 v[140:141], v[140:141], v[188:189]
	v_cvt_f32_ubyte0_e32 v138, v139
	v_rcp_iflag_f32_e32 v144, v144
	v_pk_mul_f32 v[114:115], v[114:115], v[140:141]
	v_rcp_iflag_f32_e32 v140, v138
	v_cvt_f32_ubyte1_e32 v138, v139
	v_rcp_iflag_f32_e32 v141, v138
	v_cvt_f32_ubyte2_e32 v138, v139
	v_cvt_f32_ubyte3_e32 v139, v139
	v_rcp_iflag_f32_e32 v138, v138
	v_rcp_iflag_f32_e32 v139, v139
	v_cvt_f32_ubyte3_e32 v187, v142
	v_cvt_f32_ubyte2_e32 v186, v142
	v_permlane16_swap_b32_e32 v143, v35
	v_pk_mul_f32 v[144:145], v[144:145], v[186:187]
	v_cvt_f32_ubyte1_e32 v187, v143
	v_pk_mul_f32 v[116:117], v[116:117], v[144:145]
	v_cvt_f32_ubyte3_e32 v145, v143
	v_cvt_f32_ubyte2_e32 v144, v143
	v_pk_mul_f32 v[138:139], v[138:139], v[144:145]
	v_cvt_f32_ubyte0_e32 v186, v143
	v_pk_mul_f32 v[112:113], v[112:113], v[138:139]
	v_cvt_f32_ubyte0_e32 v138, v190
	v_cvt_f32_ubyte1_e32 v139, v190
	v_pk_mul_f32 v[140:141], v[140:141], v[186:187]
	v_rcp_iflag_f32_e32 v138, v138
	v_rcp_iflag_f32_e32 v139, v139
	v_pk_mul_f32 v[110:111], v[110:111], v[140:141]
	v_cvt_f32_ubyte2_e32 v140, v190
	v_cvt_f32_ubyte3_e32 v141, v190
	v_rcp_iflag_f32_e32 v140, v140
	v_rcp_iflag_f32_e32 v141, v141
	v_cvt_f32_ubyte1_e32 v145, v1
	v_cvt_f32_ubyte0_e32 v144, v1
	v_cvt_f32_ubyte3_e32 v143, v1
	v_cvt_f32_ubyte2_e32 v142, v1
	v_pk_mul_f32 v[138:139], v[138:139], v[144:145]
	v_cvt_f32_ubyte0_e32 v1, v191
	v_pk_mul_f32 v[106:107], v[106:107], v[138:139]
	v_rcp_iflag_f32_e32 v138, v1
	v_cvt_f32_ubyte1_e32 v1, v191
	v_pk_mul_f32 v[140:141], v[140:141], v[142:143]
	v_rcp_iflag_f32_e32 v139, v1
	v_cvt_f32_ubyte2_e32 v1, v191
	v_pk_mul_f32 v[108:109], v[108:109], v[140:141]
	v_rcp_iflag_f32_e32 v140, v1
	v_cvt_f32_ubyte3_e32 v1, v191
	v_rcp_iflag_f32_e32 v141, v1
	v_addc_co_u32_e32 v151, vcc, 0, v37, vcc
	v_add_co_u32_e32 v152, vcc, s13, v36
	v_cvt_f32_ubyte3_e32 v143, v35
	v_cvt_f32_ubyte2_e32 v142, v35
	v_cvt_f32_ubyte1_e32 v145, v35
	v_cvt_f32_ubyte0_e32 v144, v35
	v_addc_co_u32_e32 v153, vcc, 0, v37, vcc
	v_pk_mul_f32 v[138:139], v[138:139], v[144:145]
	v_pk_mul_f32 v[140:141], v[140:141], v[142:143]
	global_load_dwordx4 v[134:137], v[150:151], off
	global_load_dwordx4 v[146:149], v[152:153], off
	v_pk_mul_f32 v[104:105], v[104:105], v[140:141]
	v_pk_mul_f32 v[102:103], v[102:103], v[138:139]
	s_mov_b32 s13, 0x1e1000
	s_waitcnt vmcnt(2)
	global_load_dwordx4 v[142:145], v[150:151], off offset:128
	global_load_dwordx4 v[138:141], v[152:153], off offset:128
	v_mov_b32_e32 v186, v160
	s_nop 1
	v_permlane16_swap_b32_e32 v158, v186
	v_cvt_f32_ubyte0_e32 v150, v158
	v_cvt_f32_ubyte1_e32 v151, v158
	v_rcp_iflag_f32_e32 v150, v150
	v_rcp_iflag_f32_e32 v151, v151
	v_mov_b32_e32 v1, v156
	v_cvt_f32_ubyte2_e32 v152, v158
	v_cvt_f32_ubyte3_e32 v153, v158
	v_permlane16_swap_b32_e32 v154, v1
	v_rcp_iflag_f32_e32 v152, v152
	v_rcp_iflag_f32_e32 v153, v153
	v_mov_b32_e32 v187, v161
	v_cvt_f32_ubyte1_e32 v161, v154
	v_cvt_f32_ubyte0_e32 v160, v154
	v_permlane16_swap_b32_e32 v159, v187
	v_pk_mul_f32 v[150:151], v[150:151], v[160:161]
	v_mov_b32_e32 v35, v157
	v_cvt_f32_ubyte3_e32 v157, v154
	v_cvt_f32_ubyte2_e32 v156, v154
	v_pk_mul_f32 v[82:83], v[82:83], v[150:151]
	v_cvt_f32_ubyte0_e32 v150, v159
	v_cvt_f32_ubyte1_e32 v151, v159
	v_pk_mul_f32 v[152:153], v[152:153], v[156:157]
	v_rcp_iflag_f32_e32 v150, v150
	v_rcp_iflag_f32_e32 v151, v151
	v_pk_mul_f32 v[84:85], v[84:85], v[152:153]
	v_cvt_f32_ubyte2_e32 v152, v159
	v_cvt_f32_ubyte3_e32 v153, v159
	v_permlane16_swap_b32_e32 v155, v35
	v_rcp_iflag_f32_e32 v152, v152
	v_rcp_iflag_f32_e32 v153, v153
	v_cvt_f32_ubyte1_e32 v159, v155
	v_cvt_f32_ubyte0_e32 v158, v155
	v_pk_mul_f32 v[150:151], v[150:151], v[158:159]
	v_cvt_f32_ubyte3_e32 v157, v155
	v_cvt_f32_ubyte2_e32 v156, v155
	v_pk_mul_f32 v[78:79], v[78:79], v[150:151]
	v_cvt_f32_ubyte0_e32 v150, v186
	v_cvt_f32_ubyte1_e32 v151, v186
	v_pk_mul_f32 v[152:153], v[152:153], v[156:157]
	v_rcp_iflag_f32_e32 v150, v150
	v_rcp_iflag_f32_e32 v151, v151
	v_pk_mul_f32 v[80:81], v[80:81], v[152:153]
	v_cvt_f32_ubyte2_e32 v152, v186
	v_cvt_f32_ubyte3_e32 v153, v186
	v_rcp_iflag_f32_e32 v152, v152
	v_rcp_iflag_f32_e32 v153, v153
	v_cvt_f32_ubyte1_e32 v157, v1
	v_cvt_f32_ubyte0_e32 v156, v1
	v_cvt_f32_ubyte3_e32 v155, v1
	v_cvt_f32_ubyte2_e32 v154, v1
	v_pk_mul_f32 v[150:151], v[150:151], v[156:157]
	v_cvt_f32_ubyte0_e32 v1, v187
	v_pk_mul_f32 v[74:75], v[74:75], v[150:151]
	v_rcp_iflag_f32_e32 v150, v1
	v_cvt_f32_ubyte1_e32 v1, v187
	v_pk_mul_f32 v[152:153], v[152:153], v[154:155]
	v_rcp_iflag_f32_e32 v151, v1
	v_cvt_f32_ubyte2_e32 v1, v187
	v_pk_mul_f32 v[76:77], v[76:77], v[152:153]
	v_rcp_iflag_f32_e32 v152, v1
	v_cvt_f32_ubyte3_e32 v1, v187
	v_rcp_iflag_f32_e32 v153, v1
	v_cvt_f32_ubyte3_e32 v155, v35
	v_cvt_f32_ubyte2_e32 v154, v35
	v_cvt_f32_ubyte1_e32 v157, v35
	v_cvt_f32_ubyte0_e32 v156, v35
	v_pk_mul_f32 v[150:151], v[150:151], v[156:157]
	v_pk_mul_f32 v[152:153], v[152:153], v[154:155]
	v_pk_mul_f32 v[70:71], v[70:71], v[150:151]
	v_pk_mul_f32 v[72:73], v[72:73], v[152:153]
	v_add_co_u32_e32 v158, vcc, s13, v36
	s_waitcnt vmcnt(2)
	s_mov_b32 s13, 0x1e0000
	v_mov_b32_e32 v188, v136
	s_nop 1
	v_permlane16_swap_b32_e32 v134, v188
	v_mov_b32_e32 v189, v137
	v_cvt_f32_ubyte0_e32 v136, v134
	v_cvt_f32_ubyte1_e32 v137, v134
	v_rcp_iflag_f32_e32 v136, v136
	v_rcp_iflag_f32_e32 v137, v137
	v_mov_b32_e32 v1, v148
	s_nop 1
	v_permlane16_swap_b32_e32 v146, v1
	v_permlane16_swap_b32_e32 v135, v189
	v_cvt_f32_ubyte2_e32 v148, v134
	v_cvt_f32_ubyte3_e32 v134, v134
	v_cvt_f32_ubyte1_e32 v187, v146
	v_cvt_f32_ubyte0_e32 v186, v146
	v_mov_b32_e32 v35, v149
	v_rcp_iflag_f32_e32 v149, v134
	v_pk_mul_f32 v[136:137], v[136:137], v[186:187]
	v_cvt_f32_ubyte0_e32 v134, v135
	v_rcp_iflag_f32_e32 v148, v148
	v_pk_mul_f32 v[66:67], v[66:67], v[136:137]
	v_rcp_iflag_f32_e32 v136, v134
	v_cvt_f32_ubyte1_e32 v134, v135
	v_rcp_iflag_f32_e32 v137, v134
	v_cvt_f32_ubyte2_e32 v134, v135
	v_cvt_f32_ubyte3_e32 v135, v135
	v_rcp_iflag_f32_e32 v134, v134
	v_rcp_iflag_f32_e32 v135, v135
	v_cvt_f32_ubyte3_e32 v161, v146
	v_cvt_f32_ubyte2_e32 v160, v146
	v_permlane16_swap_b32_e32 v147, v35
	v_pk_mul_f32 v[148:149], v[148:149], v[160:161]
	v_cvt_f32_ubyte1_e32 v161, v147
	v_pk_mul_f32 v[68:69], v[68:69], v[148:149]
	v_cvt_f32_ubyte3_e32 v149, v147
	v_cvt_f32_ubyte2_e32 v148, v147
	v_pk_mul_f32 v[134:135], v[134:135], v[148:149]
	v_cvt_f32_ubyte0_e32 v160, v147
	v_pk_mul_f32 v[64:65], v[64:65], v[134:135]
	v_cvt_f32_ubyte0_e32 v134, v188
	v_cvt_f32_ubyte1_e32 v135, v188
	v_pk_mul_f32 v[136:137], v[136:137], v[160:161]
	v_rcp_iflag_f32_e32 v134, v134
	v_rcp_iflag_f32_e32 v135, v135
	v_pk_mul_f32 v[62:63], v[62:63], v[136:137]
	v_cvt_f32_ubyte2_e32 v136, v188
	v_cvt_f32_ubyte3_e32 v137, v188
	v_rcp_iflag_f32_e32 v136, v136
	v_rcp_iflag_f32_e32 v137, v137
	v_cvt_f32_ubyte1_e32 v149, v1
	v_cvt_f32_ubyte0_e32 v148, v1
	v_cvt_f32_ubyte3_e32 v147, v1
	v_cvt_f32_ubyte2_e32 v146, v1
	v_pk_mul_f32 v[134:135], v[134:135], v[148:149]
	v_cvt_f32_ubyte0_e32 v1, v189
	v_pk_mul_f32 v[58:59], v[58:59], v[134:135]
	v_rcp_iflag_f32_e32 v134, v1
	v_cvt_f32_ubyte1_e32 v1, v189
	v_pk_mul_f32 v[136:137], v[136:137], v[146:147]
	v_rcp_iflag_f32_e32 v135, v1
	v_cvt_f32_ubyte2_e32 v1, v189
	v_pk_mul_f32 v[60:61], v[60:61], v[136:137]
	v_rcp_iflag_f32_e32 v136, v1
	v_cvt_f32_ubyte3_e32 v1, v189
	v_rcp_iflag_f32_e32 v137, v1
	v_addc_co_u32_e32 v159, vcc, 0, v37, vcc
	v_add_co_u32_e32 v36, vcc, s13, v36
	v_cvt_f32_ubyte3_e32 v147, v35
	v_cvt_f32_ubyte2_e32 v146, v35
	v_cvt_f32_ubyte1_e32 v149, v35
	v_cvt_f32_ubyte0_e32 v148, v35
	v_addc_co_u32_e32 v37, vcc, 0, v37, vcc
	v_pk_mul_f32 v[134:135], v[134:135], v[148:149]
	v_pk_mul_f32 v[136:137], v[136:137], v[146:147]
	global_load_dwordx4 v[150:153], v[158:159], off
	global_load_dwordx4 v[154:157], v[36:37], off
	v_pk_mul_f32 v[56:57], v[56:57], v[136:137]
	v_pk_mul_f32 v[54:55], v[54:55], v[134:135]
	s_nop 0
	s_waitcnt vmcnt(2)
	global_load_dwordx4 v[146:149], v[158:159], off offset:128
	global_load_dwordx4 v[134:137], v[36:37], off offset:128
	v_mov_b32_e32 v160, v144
	s_nop 1
	v_permlane16_swap_b32_e32 v142, v160
	v_cvt_f32_ubyte0_e32 v36, v142
	v_cvt_f32_ubyte1_e32 v37, v142
	v_rcp_iflag_f32_e32 v36, v36
	v_rcp_iflag_f32_e32 v37, v37
	v_mov_b32_e32 v1, v140
	v_mov_b32_e32 v35, v141
	v_cvt_f32_ubyte2_e32 v140, v142
	v_cvt_f32_ubyte3_e32 v141, v142
	v_permlane16_swap_b32_e32 v138, v1
	v_rcp_iflag_f32_e32 v140, v140
	v_rcp_iflag_f32_e32 v141, v141
	v_mov_b32_e32 v161, v145
	v_cvt_f32_ubyte1_e32 v159, v138
	v_cvt_f32_ubyte0_e32 v158, v138
	v_permlane16_swap_b32_e32 v143, v161
	v_pk_mul_f32 v[36:37], v[36:37], v[158:159]
	v_cvt_f32_ubyte3_e32 v145, v138
	v_cvt_f32_ubyte2_e32 v144, v138
	v_pk_mul_f32 v[30:31], v[30:31], v[36:37]
	v_cvt_f32_ubyte0_e32 v36, v143
	v_cvt_f32_ubyte1_e32 v37, v143
	v_pk_mul_f32 v[140:141], v[140:141], v[144:145]
	v_rcp_iflag_f32_e32 v36, v36
	v_rcp_iflag_f32_e32 v37, v37
	v_cvt_f32_ubyte2_e32 v138, v143
	v_pk_mul_f32 v[32:33], v[32:33], v[140:141]
	v_rcp_iflag_f32_e32 v140, v138
	v_cvt_f32_ubyte3_e32 v138, v143
	v_permlane16_swap_b32_e32 v139, v35
	v_rcp_iflag_f32_e32 v141, v138
	v_cvt_f32_ubyte1_e32 v145, v139
	v_cvt_f32_ubyte0_e32 v144, v139
	v_pk_mul_f32 v[36:37], v[36:37], v[144:145]
	v_cvt_f32_ubyte3_e32 v143, v139
	v_cvt_f32_ubyte2_e32 v142, v139
	v_pk_mul_f32 v[26:27], v[26:27], v[36:37]
	v_cvt_f32_ubyte0_e32 v36, v160
	v_cvt_f32_ubyte1_e32 v37, v160
	v_pk_mul_f32 v[138:139], v[140:141], v[142:143]
	v_rcp_iflag_f32_e32 v36, v36
	v_rcp_iflag_f32_e32 v37, v37
	v_pk_mul_f32 v[28:29], v[28:29], v[138:139]
	v_cvt_f32_ubyte2_e32 v138, v160
	v_cvt_f32_ubyte3_e32 v139, v160
	v_rcp_iflag_f32_e32 v138, v138
	v_rcp_iflag_f32_e32 v139, v139
	v_cvt_f32_ubyte1_e32 v143, v1
	v_cvt_f32_ubyte0_e32 v142, v1
	v_cvt_f32_ubyte3_e32 v141, v1
	v_cvt_f32_ubyte2_e32 v140, v1
	v_pk_mul_f32 v[36:37], v[36:37], v[142:143]
	v_cvt_f32_ubyte0_e32 v1, v161
	v_pk_mul_f32 v[22:23], v[22:23], v[36:37]
	v_rcp_iflag_f32_e32 v36, v1
	v_cvt_f32_ubyte1_e32 v1, v161
	v_pk_mul_f32 v[138:139], v[138:139], v[140:141]
	v_rcp_iflag_f32_e32 v37, v1
	v_cvt_f32_ubyte2_e32 v1, v161
	v_pk_mul_f32 v[24:25], v[24:25], v[138:139]
	v_rcp_iflag_f32_e32 v138, v1
	v_cvt_f32_ubyte3_e32 v1, v161
	v_rcp_iflag_f32_e32 v139, v1
	v_cvt_f32_ubyte3_e32 v141, v35
	v_cvt_f32_ubyte2_e32 v140, v35
	v_cvt_f32_ubyte1_e32 v143, v35
	v_cvt_f32_ubyte0_e32 v142, v35
	v_pk_mul_f32 v[36:37], v[36:37], v[142:143]
	v_pk_mul_f32 v[138:139], v[138:139], v[140:141]
	v_pk_mul_f32 v[18:19], v[18:19], v[36:37]
	v_pk_mul_f32 v[20:21], v[20:21], v[138:139]
	s_nop 0
	s_waitcnt vmcnt(0)
	s_nop 0
	v_mov_b32_e32 v144, v152
	s_nop 1
	v_permlane16_swap_b32_e32 v150, v144
	v_cvt_f32_ubyte0_e32 v36, v150
	v_cvt_f32_ubyte1_e32 v37, v150
	v_rcp_iflag_f32_e32 v36, v36
	v_rcp_iflag_f32_e32 v37, v37
	v_mov_b32_e32 v1, v156
	v_cvt_f32_ubyte2_e32 v138, v150
	v_cvt_f32_ubyte3_e32 v139, v150
	v_permlane16_swap_b32_e32 v154, v1
	v_rcp_iflag_f32_e32 v138, v138
	v_rcp_iflag_f32_e32 v139, v139
	v_mov_b32_e32 v145, v153
	v_cvt_f32_ubyte1_e32 v143, v154
	v_cvt_f32_ubyte0_e32 v142, v154
	v_permlane16_swap_b32_e32 v151, v145
	v_pk_mul_f32 v[36:37], v[36:37], v[142:143]
	v_cvt_f32_ubyte3_e32 v141, v154
	v_cvt_f32_ubyte2_e32 v140, v154
	v_pk_mul_f32 v[50:51], v[50:51], v[36:37]
	v_cvt_f32_ubyte0_e32 v36, v151
	v_cvt_f32_ubyte1_e32 v37, v151
	v_pk_mul_f32 v[138:139], v[138:139], v[140:141]
	v_rcp_iflag_f32_e32 v36, v36
	v_rcp_iflag_f32_e32 v37, v37
	v_mov_b32_e32 v35, v157
	v_pk_mul_f32 v[52:53], v[52:53], v[138:139]
	v_cvt_f32_ubyte2_e32 v138, v151
	v_cvt_f32_ubyte3_e32 v139, v151
	v_permlane16_swap_b32_e32 v155, v35
	v_rcp_iflag_f32_e32 v138, v138
	v_rcp_iflag_f32_e32 v139, v139
	v_cvt_f32_ubyte1_e32 v143, v155
	v_cvt_f32_ubyte0_e32 v142, v155
	v_pk_mul_f32 v[36:37], v[36:37], v[142:143]
	v_cvt_f32_ubyte3_e32 v141, v155
	v_cvt_f32_ubyte2_e32 v140, v155
	v_pk_mul_f32 v[46:47], v[46:47], v[36:37]
	v_cvt_f32_ubyte0_e32 v36, v144
	v_cvt_f32_ubyte1_e32 v37, v144
	v_pk_mul_f32 v[138:139], v[138:139], v[140:141]
	v_rcp_iflag_f32_e32 v36, v36
	v_rcp_iflag_f32_e32 v37, v37
	v_pk_mul_f32 v[48:49], v[48:49], v[138:139]
	v_cvt_f32_ubyte2_e32 v138, v144
	v_cvt_f32_ubyte3_e32 v139, v144
	v_rcp_iflag_f32_e32 v138, v138
	v_rcp_iflag_f32_e32 v139, v139
	v_cvt_f32_ubyte1_e32 v143, v1
	v_cvt_f32_ubyte0_e32 v142, v1
	v_cvt_f32_ubyte3_e32 v141, v1
	v_cvt_f32_ubyte2_e32 v140, v1
	v_pk_mul_f32 v[36:37], v[36:37], v[142:143]
	v_cvt_f32_ubyte0_e32 v1, v145
	v_pk_mul_f32 v[42:43], v[42:43], v[36:37]
	v_rcp_iflag_f32_e32 v36, v1
	v_cvt_f32_ubyte1_e32 v1, v145
	v_pk_mul_f32 v[138:139], v[138:139], v[140:141]
	v_rcp_iflag_f32_e32 v37, v1
	v_cvt_f32_ubyte2_e32 v1, v145
	v_pk_mul_f32 v[44:45], v[44:45], v[138:139]
	v_rcp_iflag_f32_e32 v138, v1
	v_cvt_f32_ubyte3_e32 v1, v145
	v_rcp_iflag_f32_e32 v139, v1
	v_cvt_f32_ubyte3_e32 v141, v35
	v_cvt_f32_ubyte2_e32 v140, v35
	v_cvt_f32_ubyte1_e32 v143, v35
	v_cvt_f32_ubyte0_e32 v142, v35
	v_pk_mul_f32 v[36:37], v[36:37], v[142:143]
	v_pk_mul_f32 v[138:139], v[138:139], v[140:141]
	v_pk_mul_f32 v[38:39], v[38:39], v[36:37]
	v_pk_mul_f32 v[40:41], v[40:41], v[138:139]
	v_mov_b64_e32 v[140:141], v[136:137]
	v_mov_b64_e32 v[142:143], v[146:147]
	v_mov_b64_e32 v[138:139], v[134:135]
	v_mov_b64_e32 v[144:145], v[148:149]
	s_nop 0
	v_mov_b32_e32 v152, v148
	s_nop 1
	v_permlane16_swap_b32_e32 v146, v152
	v_cvt_f32_ubyte0_e32 v36, v146
	v_cvt_f32_ubyte1_e32 v37, v146
	v_rcp_iflag_f32_e32 v36, v36
	v_rcp_iflag_f32_e32 v37, v37
	v_mov_b32_e32 v1, v136
	v_mov_b32_e32 v35, v137
	v_cvt_f32_ubyte2_e32 v136, v146
	v_cvt_f32_ubyte3_e32 v137, v146
	v_permlane16_swap_b32_e32 v134, v1
	v_rcp_iflag_f32_e32 v136, v136
	v_rcp_iflag_f32_e32 v137, v137
	v_mov_b32_e32 v153, v149
	v_cvt_f32_ubyte1_e32 v151, v134
	v_cvt_f32_ubyte0_e32 v150, v134
	v_permlane16_swap_b32_e32 v147, v153
	v_pk_mul_f32 v[36:37], v[36:37], v[150:151]
	v_cvt_f32_ubyte3_e32 v149, v134
	v_cvt_f32_ubyte2_e32 v148, v134
	v_pk_mul_f32 v[14:15], v[14:15], v[36:37]
	v_cvt_f32_ubyte0_e32 v36, v147
	v_cvt_f32_ubyte1_e32 v37, v147
	v_pk_mul_f32 v[136:137], v[136:137], v[148:149]
	v_rcp_iflag_f32_e32 v36, v36
	v_rcp_iflag_f32_e32 v37, v37
	v_cvt_f32_ubyte2_e32 v134, v147
	v_pk_mul_f32 v[16:17], v[16:17], v[136:137]
	v_rcp_iflag_f32_e32 v136, v134
	v_cvt_f32_ubyte3_e32 v134, v147
	v_permlane16_swap_b32_e32 v135, v35
	v_rcp_iflag_f32_e32 v137, v134
	v_cvt_f32_ubyte1_e32 v149, v135
	v_cvt_f32_ubyte0_e32 v148, v135
	v_pk_mul_f32 v[36:37], v[36:37], v[148:149]
	v_cvt_f32_ubyte3_e32 v147, v135
	v_cvt_f32_ubyte2_e32 v146, v135
	v_pk_mul_f32 v[10:11], v[10:11], v[36:37]
	v_cvt_f32_ubyte0_e32 v36, v152
	v_cvt_f32_ubyte1_e32 v37, v152
	v_pk_mul_f32 v[134:135], v[136:137], v[146:147]
	v_rcp_iflag_f32_e32 v36, v36
	v_rcp_iflag_f32_e32 v37, v37
	v_pk_mul_f32 v[12:13], v[12:13], v[134:135]
	v_cvt_f32_ubyte2_e32 v134, v152
	v_cvt_f32_ubyte3_e32 v135, v152
	v_rcp_iflag_f32_e32 v134, v134
	v_rcp_iflag_f32_e32 v135, v135
	v_cvt_f32_ubyte1_e32 v147, v1
	v_cvt_f32_ubyte0_e32 v146, v1
	v_cvt_f32_ubyte3_e32 v137, v1
	v_cvt_f32_ubyte2_e32 v136, v1
	v_pk_mul_f32 v[36:37], v[36:37], v[146:147]
	v_cvt_f32_ubyte0_e32 v1, v153
	v_pk_mul_f32 v[6:7], v[6:7], v[36:37]
	v_rcp_iflag_f32_e32 v36, v1
	v_cvt_f32_ubyte1_e32 v1, v153
	v_pk_mul_f32 v[134:135], v[134:135], v[136:137]
	v_rcp_iflag_f32_e32 v37, v1
	v_cvt_f32_ubyte2_e32 v1, v153
	v_pk_mul_f32 v[8:9], v[8:9], v[134:135]
	v_rcp_iflag_f32_e32 v134, v1
	v_cvt_f32_ubyte3_e32 v1, v153
	v_rcp_iflag_f32_e32 v135, v1
	v_cvt_f32_ubyte3_e32 v137, v35
	v_cvt_f32_ubyte2_e32 v136, v35
	v_cvt_f32_ubyte1_e32 v147, v35
	v_cvt_f32_ubyte0_e32 v146, v35
	v_pk_mul_f32 v[36:37], v[36:37], v[146:147]
	v_pk_mul_f32 v[134:135], v[134:135], v[136:137]
	v_pk_mul_f32 v[2:3], v[2:3], v[36:37]
	v_pk_mul_f32 v[4:5], v[4:5], v[134:135]
	v_mov_b64_e32 v[134:135], v[138:139]
	v_mov_b64_e32 v[148:149], v[144:145]
	v_mov_b64_e32 v[136:137], v[140:141]
	v_mov_b64_e32 v[146:147], v[142:143]
	s_and_b64 vcc, exec, s[38:39]
	s_mov_b64 s[18:19], -1
	s_cbranch_vccnz .LBB0_1616
